# transposed-segment job: upper-half workgroups take the units without f32 scatter outputs (256..383), lower-half workgroups take {b, b+128}
# baseline (speedup 1.0000x reference)
.LBB0_207:
	s_or_b64 exec, exec, s[0:1]
	v_readlane_b32 s0, v239, 0
	v_readlane_b32 s1, v239, 1
	s_waitcnt lgkmcnt(0)
	s_barrier
	s_load_dwordx4 s[20:23], s[0:1], 0xd8
	s_waitcnt lgkmcnt(0)
	s_add_u32 s89, s22, 0x1b000000
	s_addc_u32 s94, s23, 0
	s_add_u32 s18, s22, 0x7000000
	s_addc_u32 s19, s23, 0
	v_readlane_b32 s0, v239, 2
	s_add_u32 s24, s22, 0x21000000
	s_mov_b32 s65, s0
	s_addc_u32 s25, s23, 0
	v_readlane_b32 s6, v239, 7
	s_cmp_lt_i32 s65, s6
	v_readlane_b32 s1, v239, 3
	s_cselect_b64 s[86:87], -1, 0
	s_cmp_ge_i32 s65, s6
	s_cselect_b64 s[0:1], -1, 0
	s_add_u32 s95, s22, 0x1200000
	s_addc_u32 s96, s23, 0
	v_writelane_b32 v239, s0, 44
	s_cmpk_lt_i32 s65, 0x180
	s_mov_b32 s60, 0
	v_writelane_b32 v239, s1, 45
	s_cselect_b64 s[0:1], -1, 0
	v_writelane_b32 v239, s0, 52
	s_nop 1
	v_writelane_b32 v239, s1, 53
	s_cmpk_ge_i32 s65, 0x80
	s_cselect_b32 s1, 0x80, 0
	s_add_i32 s1, s65, s1
	s_mul_i32 s0, s1, 0x2aab
	s_lshr_b32 s0, s0, 16
	s_mul_i32 s2, s0, 6
	s_sub_i32 s2, s1, s2
	s_add_u32 s97, s20, 0x4000000
	s_addc_u32 s28, s21, 0
	s_add_u32 s29, s20, 0xc000000
	s_addc_u32 s36, s21, 0
	s_add_u32 s34, s22, 0x6c80000
	s_addc_u32 s35, s23, 0
	s_sext_i32_i16 s1, s2
	s_add_u32 s37, s22, 0xf400000
	v_writelane_b32 v239, s1, 54
	s_sext_i32_i16 s1, s0
	s_addc_u32 s4, s23, 0
	v_writelane_b32 v239, s1, 55
	s_cmpk_lt_i32 s65, 0x900
	s_mul_hi_i32 s1, s65, 0x38e38e39
	s_cselect_b64 s[8:9], -1, 0
	s_lshr_b32 s3, s1, 31
	s_ashr_i32 s1, s1, 9
	s_add_i32 s1, s1, s3
	s_mulk_i32 s1, 0x900
	s_sub_i32 s1, s65, s1
	s_bfe_u32 s3, s1, 0x3001c
	s_add_i32 s3, s1, s3
	v_writelane_b32 v239, s8, 56
	s_sext_i32_i16 s5, s3
	s_and_b32 s3, s3, 0xfff8
	v_writelane_b32 v239, s9, 57
	s_ashr_i32 s8, s5, 3
	s_sub_i32 s9, s1, s3
	s_add_u32 s5, s22, 0x6c00000
	s_addc_u32 s70, s23, 0
	s_sub_i32 s71, s65, s6
	s_add_u32 s1, s22, 0x1d000000
	s_addc_u32 s69, s23, 0
	s_add_u32 s50, s22, 0x1f000000
	s_addc_u32 s51, s23, 0
	s_cmpk_lt_i32 s71, 0x200
	v_writelane_b32 v239, s1, 58
	s_cselect_b64 s[6:7], -1, 0
	s_ashr_i32 s1, s71, 31
	s_lshr_b32 s1, s1, 25
	s_add_i32 s1, s71, s1
	s_ashr_i32 s12, s1, 7
	s_and_b32 s1, s1, 0xffffff80
	s_sub_i32 s1, s71, s1
	s_lshr_b32 s3, s1, 31
	s_add_i32 s3, s1, s3
	v_writelane_b32 v239, s6, 60
	s_ashr_i32 s14, s3, 1
	s_and_b32 s3, s3, -2
	v_writelane_b32 v239, s7, 61
	s_mov_b32 s6, s14
	s_sub_i32 s16, s1, s3
	s_ashr_i32 s15, s14, 31
	v_writelane_b32 v239, s6, 62
	s_ashr_i32 s17, s16, 31
	s_ashr_i32 s13, s12, 31
	v_writelane_b32 v239, s7, 63
	s_lshl_b64 s[6:7], s[14:15], 19
	s_add_u32 s1, s89, s6
	s_mov_b32 s6, s12
	s_addc_u32 s3, s94, s7
	v_writelane_b32 v238, s6, 0
	s_sext_i32_i16 s10, s9
	s_nop 0
	v_writelane_b32 v238, s7, 1
	s_lshl_b64 s[6:7], s[12:13], 9
	s_add_u32 s12, s1, s6
	s_mov_b32 s6, s16
	s_addc_u32 s13, s3, s7
	v_writelane_b32 v238, s6, 2
	s_nop 1
	v_writelane_b32 v238, s7, 3
	s_lshl_b64 s[6:7], s[16:17], 17
	s_add_u32 s6, s5, s6
	s_addc_u32 s7, s70, s7
	s_add_u32 s14, s12, 0x40000
	s_addc_u32 s15, s13, 0
	v_writelane_b32 v238, s14, 4
	s_nop 1
	v_writelane_b32 v238, s15, 5
	s_add_u32 s14, s6, 0x10000
	v_writelane_b32 v238, s6, 6
	s_addc_u32 s15, s7, 0
	s_nop 0
	v_writelane_b32 v238, s7, 7
	v_writelane_b32 v238, s14, 8
	s_add_u32 s6, s12, 0x40080
	s_nop 0
	v_writelane_b32 v238, s15, 9
	v_writelane_b32 v238, s12, 10
	s_addc_u32 s7, s13, 0
	s_bfe_i64 s[0:1], s[0:1], 0x100000
	v_writelane_b32 v238, s13, 11
	v_writelane_b32 v238, s6, 12
	s_bfe_i64 s[2:3], s[2:3], 0x100000
	s_lshl_b64 s[0:1], s[0:1], 19
	v_writelane_b32 v238, s7, 13
	s_add_u32 s6, s89, s0
	s_addc_u32 s7, s94, s1
	s_lshl_b64 s[0:1], s[2:3], 19
	s_add_u32 s0, s95, s0
	s_addc_u32 s1, s96, s1
	s_add_u32 s2, s6, 0x40000
	s_addc_u32 s3, s7, 0
	v_writelane_b32 v238, s2, 14
	s_nop 1
	v_writelane_b32 v238, s3, 15
	s_add_u32 s2, s0, 0x40000
	v_writelane_b32 v238, s0, 16
	s_addc_u32 s3, s1, 0
	s_nop 0
	v_writelane_b32 v238, s1, 17
	v_writelane_b32 v238, s2, 18
	s_add_u32 s0, s6, 0x40080
	s_nop 0
	v_writelane_b32 v238, s3, 19
	v_writelane_b32 v238, s6, 20
	s_addc_u32 s1, s7, 0
	s_cmp_lt_i32 s10, 0
	v_writelane_b32 v238, s7, 21
	v_writelane_b32 v238, s0, 22
	s_nop 1
	v_writelane_b32 v238, s1, 23
	s_movk_i32 s0, 0x121
	s_cselect_b32 s0, s0, 0x120
	s_mul_i32 s0, s0, s9
	s_add_i32 s0, s0, s8
	s_sext_i32_i16 s1, s0
	s_mulk_i32 s1, 0xe39
	s_lshr_b32 s2, s1, 31
	s_ashr_i32 s1, s1, 20
	s_add_i32 s1, s1, s2
	s_lshl_b32 s2, s1, 3
	s_mulk_i32 s1, 0x120
	s_sub_i32 s0, s0, s1
	s_sext_i32_i16 s0, s0
	s_lshr_b32 s1, s0, 29
	s_add_i32 s1, s0, s1
	s_ashr_i32 s6, s1, 3
	s_and_b32 s1, s1, -8
	s_sub_i32 s0, s0, s1
	s_add_i32 s2, s0, s2
	s_mov_b32 s0, s6
	s_ashr_i32 s7, s6, 31
	v_writelane_b32 v238, s0, 24
	s_ashr_i32 s3, s2, 31
	s_nop 0
	v_writelane_b32 v238, s1, 25
	s_lshl_b64 s[0:1], s[6:7], 19
	s_add_u32 s6, s22, s0
	s_mov_b32 s0, s2
	s_addc_u32 s7, s23, s1
	v_writelane_b32 v238, s0, 26
	s_nop 1
	v_writelane_b32 v238, s1, 27
	s_lshl_b64 s[0:1], s[2:3], 19
	s_add_u32 s0, s89, s0
	s_addc_u32 s1, s94, s1
	s_add_u32 s2, s6, 0x40000
	s_addc_u32 s3, s7, 0
	v_writelane_b32 v238, s2, 28
	s_nop 1
	v_writelane_b32 v238, s3, 29
	s_add_u32 s2, s0, 0x40000
	v_writelane_b32 v238, s0, 30
	s_addc_u32 s3, s1, 0
	s_nop 0
	v_writelane_b32 v238, s1, 31
	v_writelane_b32 v238, s2, 32
	s_add_u32 s0, s6, 0x40080
	s_nop 0
	v_writelane_b32 v238, s3, 33
	v_writelane_b32 v238, s6, 34
	s_addc_u32 s1, s7, 0
	s_nop 0
	v_writelane_b32 v238, s7, 35
	v_writelane_b32 v238, s0, 36
	s_nop 1
	v_writelane_b32 v238, s1, 37
	v_writelane_b32 v238, s86, 38
	s_nop 1
	v_writelane_b32 v238, s87, 39
	s_branch .LBB0_210

.LBB0_218:
	s_add_i32 s54, s54, 1
	s_lshl_b32 s11, s54, 7
	s_add_i32 s11, s11, s65
	s_cmpk_ge_i32 s65, 0x80
	s_cselect_b32 s14, 0x80, 0
	s_add_i32 s11, s11, s14
	v_readlane_b32 s15, v239, 36
	s_cmpk_lt_i32 s11, 0x100
	s_cselect_b64 s[14:15], -1, 0
	s_cmpk_gt_i32 s11, 0xff
	s_cbranch_scc1 .LBB0_220
	s_mul_hi_i32 s10, s11, 0x2aaaaaab
	s_lshr_b32 s12, s10, 31
	s_lshr_b32 s10, s10, 6
	s_add_i32 s10, s10, s12
	s_mulk_i32 s10, 0x180
	s_sub_i32 s10, s11, s10
	s_sext_i32_i16 s11, s10
	s_mulk_i32 s11, 0x2aab
	s_lshr_b32 s12, s11, 31
	s_lshr_b32 s11, s11, 16
	s_add_i32 s11, s11, s12
	s_mul_i32 s12, s11, 6
	s_sub_i32 s10, s10, s12
	s_sext_i32_i16 s10, s10
	s_sext_i32_i16 s12, s11
